# strategy 4: one static s_setprio 1 for waves 4-7 across the P3 (MLA+DSA) attention queue, reset to 0 at the phase end
# baseline (speedup 1.0000x reference)
; #define LAS __attribute__((address_space(3)))
; #define OPQ_WS() argp_t ap = (argp_t)__builtin_amdgcn_kernarg_segment_ptr(); asm volatile("" : "+s"(ap)); unsigned char* ws = ap->ws
; __device__ __forceinline__ int opaque_tid() {
;     const unsigned hw = __builtin_amdgcn_s_getreg((5 << 11) | 4) & 63u;
;     const int w = __builtin_amdgcn_readfirstlane(*(volatile LAS int*)(uintptr_t)(LDS_WTAB + hw * 4));
;     unsigned z = 0u; asm volatile("" : "+v"(z));
;     const int lane = (int)__builtin_amdgcn_mbcnt_hi(~0u, __builtin_amdgcn_mbcnt_lo(~0u, z));
;     return (w << 6) | lane;
;     ...
;     if constexpr (PH == 3) {
;         {
;             OPQ_WS();
;             for (int rep = 0; rep < REP_A01; ++rep) {
;             unsigned* ctr = ctrl + L * 32 + 2 + 4 * rep;
;             __syncthreads();
;             for (int it = bx;;) {
;                 if (it >= 704) break;
;                 const int qb = 15 - it / 44, w = it % 44;
;                 if (w < 24) { const int b = w / 6, h = w % 6;
;                     att::AttnPtrs A{QMLA + h * 192, NUQ, KMLA + h * 128, 768, KROPE, VMLA + h * 128, 768, GATE + h * 128, GATE + h * 128, nullptr, 0.f, 0.f, (const float*)TAB};
.LBB0_1164:
	s_or_b64 exec, exec, s[0:1]
	v_readlane_b32 s2, v254, 19
	v_readlane_b32 s3, v254, 20
	s_mov_b64 s[0:1], s[86:87]
	s_andn2_b64 vcc, exec, s[2:3]
	s_waitcnt lgkmcnt(0)
	s_barrier
	s_barrier
	s_cbranch_vccnz .LBB0_1205
	s_getreg_b32 s4, hwreg(HW_REG_HW_ID, 0, 6)
	s_lshl_b32 s4, s4, 2
	s_and_b32 s4, s4, 0xfc
	s_add_i32 s4, s4, 0x20040
	v_mov_b32_e32 v0, s4
	ds_read_b32 v0, v0
	s_waitcnt lgkmcnt(0)
	v_readfirstlane_b32 s4, v0
	s_nop 3
	s_cmp_ge_u32 s4, 4
	s_cbranch_scc0 .Lp3_prio_done
	s_setprio 1
.Lp3_prio_done:
	s_load_dwordx2 s[2:3], s[0:1], 0x98
	s_mov_b32 s0, s93
	s_waitcnt lgkmcnt(0)
	s_add_u32 s4, s2, s50
	s_addc_u32 s5, s3, s51
	s_add_u32 s21, s2, 0x1fd10000
	s_addc_u32 s22, s3, 0
	s_add_u32 s23, s2, 0x1fd10500
	s_addc_u32 s24, s3, 0
	s_add_u32 s25, s2, 0x22510000
	s_addc_u32 s26, s3, 0
	s_add_u32 s27, s2, 0x1bd10600
	s_addc_u32 s28, s3, 0
	s_add_u32 s6, s2, 0x2d990000
	s_addc_u32 s7, s3, 0
	s_add_u32 s29, s2, 0x28590000
	s_addc_u32 s34, s3, 0
	s_add_u32 s35, s2, 0x2a990000
	s_addc_u32 s44, s3, 0
	s_add_u32 s8, s2, 0x1b910000
	s_addc_u32 s9, s3, 0
	s_add_u32 s45, s2, 0x2c190000
	s_addc_u32 s46, s3, 0
	s_add_u32 s47, s2, 0x1bd10000
	s_addc_u32 s48, s3, 0
	s_add_u32 s10, s2, 0x350000
	s_addc_u32 s11, s3, 0
	s_branch .LBB0_1168

; __device__ __forceinline__ unsigned xb_add(unsigned* p, unsigned v) { return __hip_atomic_fetch_add(p, v, __ATOMIC_RELAXED, __HIP_MEMORY_SCOPE_AGENT); }
; __device__ __forceinline__ void xcd_barrier(const XcdBarrier& b) {
;     asm volatile("s_waitcnt vmcnt(0)" ::: "memory");
;     __syncthreads();
;     if (opaque_tid() == 0) {
;         unsigned* bar = b.bar;
;         __builtin_amdgcn_s_waitcnt(0);
;         unsigned nloc = b.st[0], nx = b.st[1];
;         if (nloc == 0u) { xcd_barrier_complete(bar, b.x, nloc, nx); b.st[0] = nloc; b.st[1] = nx; }
;         const unsigned old = xb_add(&bar[XB_XSUB(b.x)], 1u);
;         const unsigned gen = old / nloc;
.LBB0_1205:
	s_setprio 0
	s_mov_b64 s[2:3], s[86:87]
	s_getreg_b32 s6, hwreg(HW_REG_XCC_ID, 0, 4)
	s_waitcnt vmcnt(0)
	s_barrier
	s_getreg_b32 s0, hwreg(HW_REG_HW_ID, 0, 6)
	s_lshl_b32 s0, s0, 2
	s_and_b32 s0, s0, 0xfc
	s_add_i32 s0, s0, 0x20040
	v_mov_b32_e32 v0, s0
	ds_read_b32 v0, v0
	s_waitcnt lgkmcnt(0)
	v_readfirstlane_b32 s0, v0
	v_mov_b32_e32 v0, v1
	s_nop 0
	v_mbcnt_lo_u32_b32 v0, -1, v0
	v_mbcnt_hi_u32_b32 v0, -1, v0
	v_lshl_or_b32 v0, s0, 6, v0
	v_cmp_eq_u32_e32 vcc, 0, v0
	s_and_saveexec_b64 s[0:1], vcc
	s_cbranch_execz .LBB0_1257
	v_mov_b32_e32 v0, 0x20010
	s_load_dwordx2 s[4:5], s[2:3], 0x98
	s_waitcnt vmcnt(0) expcnt(0) lgkmcnt(0)
	ds_read_b32 v3, v0
	v_mov_b32_e32 v0, 0x20014
	ds_read_b32 v0, v0
	s_and_b32 s21, s6, 15
	s_add_u32 s2, s4, 0x4200
	s_waitcnt lgkmcnt(1)
	v_cmp_ne_u32_e32 vcc, 0, v3
	s_addc_u32 s3, s5, 0
	s_cbranch_vccnz .LBB0_1221
	s_add_u32 s6, s4, 0x4400
	s_addc_u32 s7, s5, 0
	s_add_u32 s8, s4, 0x4500
	s_addc_u32 s9, s5, 0
	s_add_u32 s10, s4, 0x4600
	s_addc_u32 s11, s5, 0
	s_add_u32 s12, s4, 0x4700
	s_addc_u32 s13, s5, 0
	s_add_u32 s14, s4, 0x4800
	s_addc_u32 s15, s5, 0
	s_add_u32 s16, s4, 0x4900
	s_addc_u32 s17, s5, 0
	s_add_u32 s18, s4, 0x4a00
	s_addc_u32 s19, s5, 0
	s_add_u32 s22, s4, 0x4b00
	s_addc_u32 s23, s5, 0
	s_add_u32 s24, s4, 0x4c00
	s_addc_u32 s25, s5, 0
	s_add_u32 s26, s4, 0x4d00
	s_addc_u32 s27, s5, 0
	s_add_u32 s28, s4, 0x4e00
	s_addc_u32 s29, s5, 0
	s_add_u32 s44, s4, 0x4f00
	s_addc_u32 s45, s5, 0
	s_add_u32 s46, s4, 0x5000
	s_addc_u32 s47, s5, 0
	s_add_u32 s48, s4, 0x5100
	s_addc_u32 s49, s5, 0
	s_add_u32 s50, s4, 0x5200
	s_addc_u32 s51, s5, 0
	s_add_u32 s52, s4, 0x5300
	s_addc_u32 s53, s5, 0
	s_mov_b32 s33, 1
	s_branch .LBB0_1209
